# filler items rebalanced over GEMM tail slots: G3 tails OUT|GU2 only, hl=1 tail D2(l0)|GU1(l1), hl=2 tail D1(l1)|IN(l1)|KV(l1), previously idle hl=3 tail converts D2(l1)
# speedup vs baseline: 1.0145x; 1.0001x over previous
.LBB0_127:
	v_readlane_b32 s4, v253, 12
	v_readlane_b32 s5, v253, 13
	s_mov_b64 s[0:1], s[76:77]
	v_mov_b32_e32 v0, v204
	s_andn2_b64 vcc, exec, s[4:5]
	s_cbranch_vccnz .LBB0_251
	v_ashrrev_i32_e32 v2, 6, v0
	v_readlane_b32 s4, v253, 14
	s_nop 1
	v_add_u32_e32 v11, s4, v2
	s_movk_i32 s96, 0x2b00
	s_movk_i32 s97, 0xa00
	s_cmp_eq_u32 s75, 3
	s_cselect_b32 s96, 0x580, s96
	s_cselect_b32 s97, 0x7fffffff, s97
	v_cmp_gt_i32_e32 vcc, s96, v11
	s_and_saveexec_b64 s[24:25], vcc
	s_cbranch_execz .LBB0_250
	v_and_b32_e32 v10, 63, v0
	v_bfe_u32 v12, v0, 3, 3
	v_lshlrev_b32_e32 v3, 2, v0
	v_lshlrev_b32_e32 v0, 3, v0
	v_and_b32_e32 v14, 28, v3
	s_movk_i32 s4, 0x84
	v_mov_b32_e32 v3, 0x840
	v_and_b32_e32 v16, 56, v0
	v_lshl_add_u32 v2, v2, 14, 0
	v_mad_u32_u24 v29, v12, s4, v3
	v_mul_u32_u24_e32 v0, 0x84, v16
	v_lshlrev_b32_e32 v3, 2, v12
	v_lshl_add_u32 v15, v14, 2, v2
	v_mul_u32_u24_e32 v17, 0x84, v12
	v_or_b32_e32 v26, 8, v12
	v_mad_u32_u24 v27, v12, s4, v252
	v_or_b32_e32 v28, 16, v12
	v_or_b32_e32 v30, 24, v12
	v_or_b32_e32 v31, 32, v12
	v_or_b32_e32 v32, 40, v12
	v_or_b32_e32 v33, 48, v12
	v_or_b32_e32 v34, 56, v12
	v_add3_u32 v35, v2, v0, v3
	v_mov_b32_e32 v13, v1
	s_mov_b64 s[46:47], 0
	s_branch .LBB0_134

.LBB0_133:
	s_or_b64 exec, exec, s[48:49]
	v_add_u32_e32 v11, s95, v11
	v_cmp_le_i32_e32 vcc, s96, v11
	s_or_b64 s[46:47], vcc, s[46:47]
	s_andn2_b64 exec, exec, s[46:47]
	s_cbranch_execz .LBB0_250
.LBB0_134:
	s_mov_b32 s4, 0xffffc300
	s_cmp_eq_u32 s75, 3
	s_cselect_b32 s4, 0xffffd980, s4
	v_mov_b32_e32 v120, 0xfffff600
	v_mov_b32_e32 v121, s4
	v_cmp_gt_i32_e32 vcc, s97, v11
	s_nop 0
	v_cndmask_b32_e32 v120, v120, v121, vcc
	v_add_u32_e32 v120, v120, v11
	s_movk_i32 s4, 0xdeff
	v_cmp_lt_i32_e32 vcc, s4, v120
	s_and_saveexec_b64 s[4:5], vcc
	s_xor_b64 s[40:41], exec, s[4:5]
	s_cbranch_execz .LBB0_170
	v_subrev_co_u32_e32 v0, vcc, 0xffffdf00, v120
	s_movk_i32 s4, 0xdeff
	s_mov_b64 s[38:39], vcc
	v_cmp_lt_u32_e32 vcc, s4, v120
	s_movk_i32 s4, 0x1080
	s_nop 0
	v_cndmask_b32_e32 v0, v120, v0, vcc
	v_add_u32_e32 v2, 0xef80, v0
	v_cmp_gt_u32_e32 vcc, s4, v0
	s_mov_b32 s4, 0xf83f
	s_nop 0
	v_cndmask_b32_e32 v3, v2, v0, vcc
	v_mul_u32_u24_sdwa v2, v3, s4 dst_sel:DWORD dst_unused:UNUSED_PAD src0_sel:WORD_0 src1_sel:DWORD
	v_lshrrev_b32_e32 v2, 25, v2
	v_mul_lo_u16_e32 v4, 0x210, v2
	v_sub_u16_e32 v3, v3, v4
	v_and_b32_e32 v4, 0x3fc, v3
	s_movk_i32 s4, 0x200
	v_cmp_ne_u32_e32 vcc, s4, v4
	s_and_saveexec_b64 s[42:43], vcc
	s_cbranch_execz .LBB0_169
	s_movk_i32 s4, 0x107f
	v_cmp_lt_u32_e32 vcc, s4, v0
	v_and_b32_e32 v20, 0xffff, v2
	s_movk_i32 s4, 0x200
	v_cndmask_b32_e64 v21, 0, 1, vcc
	v_lshlrev_b32_e32 v0, 3, v21
	global_load_dwordx2 v[18:19], v0, s[0:1] offset:32
	v_cndmask_b32_e64 v0, 0, 8, s[38:39]
	v_add_lshl_u32 v0, v0, v20, 23
	v_mov_b32_e32 v2, 0
	v_cmp_gt_u16_e32 vcc, s4, v3
	v_lshlrev_b32_e32 v8, 4, v10
	v_mov_b32_e32 v4, 0
	v_mov_b32_e32 v5, 0
	v_mov_b32_e32 v6, 0
	v_mov_b32_e32 v7, 0
	s_waitcnt vmcnt(0)
	v_lshl_add_u64 v[18:19], v[18:19], 0, v[0:1]
	v_lshlrev_b32_e32 v0, 14, v3
	v_lshl_add_u64 v[24:25], v[18:19], 0, v[0:1]
	s_and_saveexec_b64 s[48:49], vcc
	s_cbranch_execz .LBB0_138
	v_mov_b32_e32 v9, v1
	v_lshl_add_u64 v[4:5], v[24:25], 0, v[8:9]
	global_load_dwordx4 v[4:7], v[4:5], off

.LBB0_170:
	s_andn2_saveexec_b64 s[48:49], s[40:41]
	s_cbranch_execz .LBB0_133
	v_add_u32_e32 v0, 0x6f00, v120
	s_mov_b32 s4, 0xd20d20d3
	v_mul_hi_i32 v2, v0, s4
	s_load_dwordx2 s[4:5], s[0:1], 0xd0
	v_add_u32_e32 v2, v2, v0
	v_lshrrev_b32_e32 v3, 31, v2
	v_ashrrev_i32_e32 v2, 13, v2
	v_add_u32_e32 v22, v2, v3
	v_mul_i32_i24_e32 v2, 0x2700, v22
	v_sub_u32_e32 v0, v0, v2
	s_waitcnt lgkmcnt(0)
	v_mov_b64_e32 v[2:3], s[4:5]
	s_mov_b32 s4, 0x2800000
	v_mad_i64_i32 v[2:3], s[4:5], v22, s4, v[2:3]
	s_mov_b64 s[4:5], 0x100000
	s_nop 0
	v_lshl_add_u64 v[18:19], v[2:3], 0, s[4:5]
	s_movk_i32 s4, 0xaff
	v_ashrrev_i32_e32 v23, 31, v22
	v_cmp_lt_i32_e32 vcc, s4, v0
	s_and_saveexec_b64 s[4:5], vcc
	s_xor_b64 s[40:41], exec, s[4:5]
	s_cbranch_execz .LBB0_231
	s_movk_i32 s4, 0x107f
	v_cmp_lt_u32_e32 vcc, s4, v0
	s_and_saveexec_b64 s[4:5], vcc
	s_xor_b64 s[42:43], exec, s[4:5]
	s_cbranch_execz .LBB0_228
	s_movk_i32 s4, 0x14ff
	v_cmp_lt_u32_e32 vcc, s4, v0
	s_and_saveexec_b64 s[4:5], vcc
	s_xor_b64 s[50:51], exec, s[4:5]
	s_cbranch_execz .LBB0_199
	s_movk_i32 s4, 0x167f
	v_cmp_lt_u32_e32 vcc, s4, v0
	s_and_saveexec_b64 s[4:5], vcc
	s_xor_b64 s[56:57], exec, s[4:5]
	s_cbranch_execz .LBB0_196
	s_movk_i32 s4, 0x217f
	v_cmp_lt_u32_e32 vcc, s4, v0
	s_and_saveexec_b64 s[4:5], vcc
	s_xor_b64 s[38:39], exec, s[4:5]
	s_cbranch_execz .LBB0_177
	s_load_dwordx2 s[4:5], s[0:1], 0xc0
	v_lshlrev_b32_e32 v2, 5, v0
	v_lshlrev_b32_e32 v0, 1, v0
	v_and_b32_e32 v4, 0x3e0, v2
	v_and_b32_e32 v0, 0x7fffffc0, v0
	s_waitcnt lgkmcnt(0)
	v_mov_b64_e32 v[2:3], s[4:5]
	s_mov_b32 s4, 0xb00000
	v_mad_i64_i32 v[6:7], s[4:5], v22, s4, v[2:3]
	v_add_u32_e32 v2, 0xffffbd00, v0
	v_lshlrev_b32_e32 v0, 2, v4
	v_lshl_add_u64 v[6:7], v[6:7], 0, v[0:1]
	v_lshlrev_b32_e32 v0, 2, v14
	v_lshl_add_u64 v[20:21], v[6:7], 0, v[0:1]
	v_or_b32_e32 v0, v2, v12
	v_lshlrev_b64 v[6:7], 12, v[0:1]
	v_lshl_add_u64 v[6:7], v[20:21], 0, v[6:7]
	global_load_dwordx4 v[6:9], v[6:7], off
	v_add_u32_e32 v3, v15, v17
	v_or_b32_e32 v0, v2, v26
	s_mov_b64 s[4:5], 0x2200000
	s_waitcnt vmcnt(0)
	ds_write2_b32 v3, v6, v7 offset1:1
	ds_write2_b32 v3, v8, v9 offset0:2 offset1:3
	v_lshlrev_b64 v[6:7], 12, v[0:1]
	v_lshl_add_u64 v[6:7], v[20:21], 0, v[6:7]
	global_load_dwordx4 v[6:9], v[6:7], off
	v_add_u32_e32 v0, 0x420, v3
	s_waitcnt vmcnt(0)
	ds_write2_b32 v0, v6, v7 offset1:1
	v_add_u32_e32 v0, 0x428, v3
	ds_write2_b32 v0, v8, v9 offset1:1
	v_or_b32_e32 v0, v2, v28
	v_lshlrev_b64 v[6:7], 12, v[0:1]
	v_lshl_add_u64 v[6:7], v[20:21], 0, v[6:7]
	global_load_dwordx4 v[6:9], v[6:7], off
	v_add_u32_e32 v0, 0x840, v3
	s_waitcnt vmcnt(0)
	ds_write2_b32 v0, v6, v7 offset1:1
	v_add_u32_e32 v0, 0x848, v3
	ds_write2_b32 v0, v8, v9 offset1:1
	v_or_b32_e32 v0, v2, v30
	v_lshlrev_b64 v[6:7], 12, v[0:1]
	v_lshl_add_u64 v[6:7], v[20:21], 0, v[6:7]
	global_load_dwordx4 v[6:9], v[6:7], off
	v_add_u32_e32 v0, 0xc60, v3
	s_waitcnt vmcnt(0)
	ds_write2_b32 v0, v6, v7 offset1:1
	v_add_u32_e32 v0, 0xc68, v3
	ds_write2_b32 v0, v8, v9 offset1:1
	v_or_b32_e32 v0, v2, v31
	v_lshlrev_b64 v[6:7], 12, v[0:1]
	v_lshl_add_u64 v[6:7], v[20:21], 0, v[6:7]
	global_load_dwordx4 v[6:9], v[6:7], off
	v_add_u32_e32 v0, 0x1080, v3
	s_waitcnt vmcnt(0)
	ds_write2_b32 v0, v6, v7 offset1:1
	v_add_u32_e32 v0, 0x1088, v3
	ds_write2_b32 v0, v8, v9 offset1:1
	v_or_b32_e32 v0, v2, v32
	v_lshlrev_b64 v[6:7], 12, v[0:1]
	v_lshl_add_u64 v[6:7], v[20:21], 0, v[6:7]
	global_load_dwordx4 v[6:9], v[6:7], off
	v_add_u32_e32 v0, 0x14a0, v3
	s_waitcnt vmcnt(0)
	ds_write2_b32 v0, v6, v7 offset1:1
	v_add_u32_e32 v0, 0x14a8, v3
	ds_write2_b32 v0, v8, v9 offset1:1
	v_or_b32_e32 v0, v2, v33
	v_lshlrev_b64 v[6:7], 12, v[0:1]
	v_lshl_add_u64 v[6:7], v[20:21], 0, v[6:7]
	global_load_dwordx4 v[6:9], v[6:7], off
	v_add_u32_e32 v0, 0x18c0, v3
	s_waitcnt vmcnt(0)
	ds_write2_b32 v0, v6, v7 offset1:1
	v_add_u32_e32 v0, 0x18c8, v3
	ds_write2_b32 v0, v8, v9 offset1:1
	v_or_b32_e32 v0, v2, v34
	v_lshlrev_b64 v[6:7], 12, v[0:1]
	v_lshl_add_u64 v[6:7], v[20:21], 0, v[6:7]
	global_load_dwordx4 v[6:9], v[6:7], off
	v_add_u32_e32 v0, 0x1ce0, v3
	s_waitcnt vmcnt(0)
	ds_write2_b32 v0, v6, v7 offset1:1
	v_add_u32_e32 v0, 0x1ce8, v3
	ds_write2_b32 v0, v8, v9 offset1:1
	s_waitcnt lgkmcnt(0)
	v_mov_b32_e32 v3, v1
	v_lshl_add_u64 v[2:3], v[2:3], 1, v[18:19]
	ds_read2_b32 v[18:19], v35 offset0:33 offset1:41
	ds_read2_b32 v[20:21], v35 offset1:8
	v_lshlrev_b32_e32 v0, 1, v16
	ds_read2_b32 v[22:23], v35 offset0:66 offset1:74
	ds_read2_b32 v[24:25], v35 offset0:99 offset1:107
	v_lshl_add_u64 v[2:3], v[2:3], 0, v[0:1]
	s_waitcnt lgkmcnt(3)
	v_bfe_u32 v5, v18, 16, 1
	s_waitcnt lgkmcnt(2)
	v_bfe_u32 v0, v20, 16, 1
	v_add3_u32 v0, v20, v0, s91
	v_lshrrev_b32_e32 v0, 16, v0
	v_add3_u32 v5, v18, v5, s91
	ds_read2_b32 v[36:37], v35 offset0:132 offset1:140
	ds_read2_b32 v[38:39], v35 offset0:165 offset1:173
	v_and_or_b32 v6, v5, s92, v0
	s_waitcnt lgkmcnt(3)
	v_bfe_u32 v0, v22, 16, 1
	v_add3_u32 v0, v22, v0, s91
	s_waitcnt lgkmcnt(2)
	v_bfe_u32 v5, v24, 16, 1
	v_lshrrev_b32_e32 v0, 16, v0
	v_add3_u32 v5, v24, v5, s91
	ds_read2_b32 v[40:41], v35 offset0:198 offset1:206
	ds_read2_b32 v[42:43], v35 offset0:231 offset1:239
	v_and_or_b32 v7, v5, s92, v0
	s_waitcnt lgkmcnt(3)
	v_bfe_u32 v0, v36, 16, 1
	v_add3_u32 v0, v36, v0, s91
	s_waitcnt lgkmcnt(2)
	v_bfe_u32 v5, v38, 16, 1
	v_lshrrev_b32_e32 v0, 16, v0
	v_add3_u32 v5, v38, v5, s91
	v_and_or_b32 v8, v5, s92, v0
	s_waitcnt lgkmcnt(1)
	v_bfe_u32 v0, v40, 16, 1
	v_add3_u32 v0, v40, v0, s91
	s_waitcnt lgkmcnt(0)
	v_bfe_u32 v5, v42, 16, 1
	v_lshrrev_b32_e32 v0, 16, v0
	v_add3_u32 v5, v42, v5, s91
	v_and_or_b32 v9, v5, s92, v0
	v_or_b32_e32 v0, v4, v12
	v_mul_u32_u24_e32 v0, 0xb00, v0
	v_lshl_add_u64 v[2:3], v[2:3], 0, s[4:5]
	v_lshlrev_b32_e32 v0, 1, v0
	v_lshl_add_u64 v[44:45], v[2:3], 0, v[0:1]
	v_bfe_u32 v0, v21, 16, 1
	v_add3_u32 v0, v21, v0, s91
	v_bfe_u32 v5, v19, 16, 1
	v_lshrrev_b32_e32 v0, 16, v0
	v_add3_u32 v5, v19, v5, s91
	global_store_dwordx4 v[44:45], v[6:9], off
	s_nop 1
	v_and_or_b32 v6, v5, s92, v0
	v_bfe_u32 v0, v23, 16, 1
	v_add3_u32 v0, v23, v0, s91
	v_bfe_u32 v5, v25, 16, 1
	v_lshrrev_b32_e32 v0, 16, v0
	v_add3_u32 v5, v25, v5, s91
	v_and_or_b32 v7, v5, s92, v0
	v_bfe_u32 v0, v37, 16, 1
	v_add3_u32 v0, v37, v0, s91
	v_bfe_u32 v5, v39, 16, 1
	v_lshrrev_b32_e32 v0, 16, v0
	v_add3_u32 v5, v39, v5, s91
	v_and_or_b32 v8, v5, s92, v0
	v_bfe_u32 v0, v41, 16, 1
	v_add3_u32 v0, v41, v0, s91
	v_bfe_u32 v5, v43, 16, 1
	v_lshrrev_b32_e32 v0, 16, v0
	v_add3_u32 v5, v43, v5, s91
	v_and_or_b32 v9, v5, s92, v0
	v_or_b32_e32 v0, v4, v26
	v_mul_u32_u24_e32 v0, 0xb00, v0
	v_lshlrev_b32_e32 v0, 1, v0
	v_lshl_add_u64 v[18:19], v[2:3], 0, v[0:1]
	global_store_dwordx4 v[18:19], v[6:9], off
	ds_read2_b32 v[18:19], v35 offset0:16 offset1:24
	ds_read2_b32 v[20:21], v35 offset0:49 offset1:57
	ds_read2_b32 v[22:23], v35 offset0:82 offset1:90
	ds_read2_b32 v[24:25], v35 offset0:115 offset1:123
	ds_read2_b32 v[36:37], v35 offset0:148 offset1:156
	ds_read2_b32 v[38:39], v35 offset0:181 offset1:189
	ds_read2_b32 v[40:41], v35 offset0:214 offset1:222
	ds_read2_b32 v[42:43], v35 offset0:247 offset1:255
	s_waitcnt lgkmcnt(7)
	v_bfe_u32 v0, v18, 16, 1
	v_add3_u32 v0, v18, v0, s91
	s_waitcnt lgkmcnt(6)
	v_bfe_u32 v5, v20, 16, 1
	v_lshrrev_b32_e32 v0, 16, v0
	v_add3_u32 v5, v20, v5, s91
	v_and_or_b32 v6, v5, s92, v0
	s_waitcnt lgkmcnt(5)
	v_bfe_u32 v0, v22, 16, 1
	v_add3_u32 v0, v22, v0, s91
	s_waitcnt lgkmcnt(4)
	v_bfe_u32 v5, v24, 16, 1
	v_lshrrev_b32_e32 v0, 16, v0
	v_add3_u32 v5, v24, v5, s91
	v_and_or_b32 v7, v5, s92, v0
	s_waitcnt lgkmcnt(3)
	v_bfe_u32 v0, v36, 16, 1
	v_add3_u32 v0, v36, v0, s91
	s_waitcnt lgkmcnt(2)
	v_bfe_u32 v5, v38, 16, 1
	v_lshrrev_b32_e32 v0, 16, v0
	v_add3_u32 v5, v38, v5, s91
	v_and_or_b32 v8, v5, s92, v0
	s_waitcnt lgkmcnt(1)
	v_bfe_u32 v0, v40, 16, 1
	v_add3_u32 v0, v40, v0, s91
	s_waitcnt lgkmcnt(0)
	v_bfe_u32 v5, v42, 16, 1
	v_lshrrev_b32_e32 v0, 16, v0
	v_add3_u32 v5, v42, v5, s91
	v_and_or_b32 v9, v5, s92, v0
	v_or_b32_e32 v0, v4, v28
	v_mul_u32_u24_e32 v0, 0xb00, v0
	v_lshlrev_b32_e32 v0, 1, v0
	v_lshl_add_u64 v[44:45], v[2:3], 0, v[0:1]
	v_bfe_u32 v0, v19, 16, 1
	v_add3_u32 v0, v19, v0, s91
	v_bfe_u32 v5, v21, 16, 1
	v_lshrrev_b32_e32 v0, 16, v0
	v_add3_u32 v5, v21, v5, s91
	global_store_dwordx4 v[44:45], v[6:9], off
	s_nop 1
	v_and_or_b32 v6, v5, s92, v0
	v_bfe_u32 v0, v23, 16, 1
	v_add3_u32 v0, v23, v0, s91
	v_bfe_u32 v5, v25, 16, 1
	v_lshrrev_b32_e32 v0, 16, v0
	v_add3_u32 v5, v25, v5, s91
	v_and_or_b32 v7, v5, s92, v0
	v_bfe_u32 v0, v37, 16, 1
	v_add3_u32 v0, v37, v0, s91
	v_bfe_u32 v5, v39, 16, 1
	v_lshrrev_b32_e32 v0, 16, v0
	v_add3_u32 v5, v39, v5, s91
	v_and_or_b32 v8, v5, s92, v0
	v_bfe_u32 v0, v41, 16, 1
	v_add3_u32 v0, v41, v0, s91
	v_bfe_u32 v5, v43, 16, 1
	v_lshrrev_b32_e32 v0, 16, v0
	v_add3_u32 v5, v43, v5, s91
	v_and_or_b32 v9, v5, s92, v0
	v_or_b32_e32 v0, v4, v30
	v_mul_u32_u24_e32 v0, 0xb00, v0
	v_lshlrev_b32_e32 v0, 1, v0
	v_lshl_add_u64 v[2:3], v[2:3], 0, v[0:1]
	global_store_dwordx4 v[2:3], v[6:9], off
	s_waitcnt lgkmcnt(0)

.LBB0_377:
	s_andn2_b64 vcc, exec, s[0:1]
	s_cbranch_vccnz .LBB0_463
	s_mov_b64 s[0:1], s[76:77]
	v_mov_b32_e32 v0, v204
	s_and_b64 vcc, exec, s[38:39]
	s_cbranch_vccnz .LBB0_463
	v_ashrrev_i32_e32 v2, 6, v0
	v_readlane_b32 s4, v253, 14
	s_nop 1
	v_add_u32_e32 v13, s4, v2
	s_movk_i32 s4, 0x1080
	v_cmp_gt_i32_e32 vcc, s4, v13
	s_and_saveexec_b64 s[24:25], vcc
	s_cbranch_execz .LBB0_462
	v_lshlrev_b32_e32 v3, 2, v0
	v_bfe_u32 v10, v0, 3, 3
	v_and_b32_e32 v12, 28, v3
	s_movk_i32 s4, 0x84
	v_mov_b32_e32 v3, 0x840
	v_mad_u32_u24 v26, v10, s4, v252
	v_mad_u32_u24 v28, v10, s4, v3
	s_load_dwordx2 s[4:5], s[0:1], 0xd0
	v_lshlrev_b32_e32 v0, 3, v0
	v_and_b32_e32 v14, 56, v0
	v_lshl_add_u32 v2, v2, 14, 0
	v_mul_u32_u24_e32 v0, 0x84, v14
	v_lshlrev_b32_e32 v3, 2, v10
	s_waitcnt lgkmcnt(0)
	s_add_u32 s46, s4, 0x100000
	v_lshl_add_u32 v15, v12, 2, v2
	v_mul_u32_u24_e32 v24, 0x84, v10
	v_or_b32_e32 v25, 8, v10
	v_or_b32_e32 v27, 16, v10
	v_or_b32_e32 v29, 24, v10
	v_or_b32_e32 v30, 32, v10
	v_or_b32_e32 v31, 40, v10
	v_or_b32_e32 v32, 48, v10
	v_or_b32_e32 v33, 56, v10
	v_add3_u32 v34, v2, v0, v3
	s_addc_u32 s47, s5, 0
	v_mov_b32_e32 v11, v1
	s_mov_b64 s[48:49], 0
	s_branch .LBB0_383

.LBB0_382:
	s_or_b64 exec, exec, s[50:51]
	v_add_u32_e32 v13, s95, v13
	s_movk_i32 s4, 0x107f
	v_cmp_lt_i32_e32 vcc, s4, v13
	s_or_b64 s[48:49], vcc, s[48:49]
	s_andn2_b64 exec, exec, s[48:49]
	s_cbranch_execz .LBB0_462
.LBB0_383:
	v_add_u32_e32 v0, 0x2180, v13
	s_mov_b32 s4, 0xd20d20d3
	v_mul_hi_i32 v2, v0, s4
	v_add_u32_e32 v2, v2, v0
	v_lshrrev_b32_e32 v3, 31, v2
	v_ashrrev_i32_e32 v2, 13, v2
	v_add_u32_e32 v20, v2, v3
	v_mul_i32_i24_e32 v2, 0x2700, v20
	v_sub_u32_e32 v0, v0, v2
	v_mov_b64_e32 v[2:3], s[46:47]
	s_mov_b32 s4, 0x2800000
	v_mad_i64_i32 v[16:17], s[4:5], v20, s4, v[2:3]
	s_movk_i32 s4, 0xaff
	v_ashrrev_i32_e32 v21, 31, v20
	v_cmp_lt_i32_e32 vcc, s4, v0
	s_and_saveexec_b64 s[4:5], vcc
	s_xor_b64 s[40:41], exec, s[4:5]
	s_cbranch_execz .LBB0_443
	s_movk_i32 s4, 0x107f
	v_cmp_lt_u32_e32 vcc, s4, v0
	s_and_saveexec_b64 s[4:5], vcc
	s_xor_b64 s[42:43], exec, s[4:5]
	s_cbranch_execz .LBB0_440
	s_movk_i32 s4, 0x14ff
	v_cmp_lt_u32_e32 vcc, s4, v0
	s_and_saveexec_b64 s[4:5], vcc
	s_xor_b64 s[50:51], exec, s[4:5]
	s_cbranch_execz .LBB0_411
	s_movk_i32 s4, 0x167f
	v_cmp_lt_u32_e32 vcc, s4, v0
	s_and_saveexec_b64 s[4:5], vcc
	s_xor_b64 s[56:57], exec, s[4:5]
	s_cbranch_execz .LBB0_408
	s_movk_i32 s4, 0x217f
	v_cmp_lt_u32_e32 vcc, s4, v0
	s_and_saveexec_b64 s[4:5], vcc
	s_xor_b64 s[38:39], exec, s[4:5]
	s_cbranch_execz .LBB0_389
	s_load_dwordx2 s[4:5], s[0:1], 0xc0
	v_lshlrev_b32_e32 v2, 5, v0
	v_lshlrev_b32_e32 v0, 1, v0
	v_and_b32_e32 v4, 0x3e0, v2
	v_and_b32_e32 v0, 0x7fffffc0, v0
	s_waitcnt lgkmcnt(0)
	v_mov_b64_e32 v[2:3], s[4:5]
	s_mov_b32 s4, 0xb00000
	v_mad_i64_i32 v[6:7], s[4:5], v20, s4, v[2:3]
	v_add_u32_e32 v2, 0xffffbd00, v0
	v_lshlrev_b32_e32 v0, 2, v4
	v_lshl_add_u64 v[6:7], v[6:7], 0, v[0:1]
	v_lshlrev_b32_e32 v0, 2, v12
	v_lshl_add_u64 v[18:19], v[6:7], 0, v[0:1]
	v_or_b32_e32 v0, v2, v10
	v_lshlrev_b64 v[6:7], 12, v[0:1]
	v_lshl_add_u64 v[6:7], v[18:19], 0, v[6:7]
	global_load_dwordx4 v[6:9], v[6:7], off
	v_add_u32_e32 v3, v15, v24
	v_or_b32_e32 v0, v2, v25
	s_mov_b64 s[4:5], 0x2200000
	s_waitcnt vmcnt(0)
	ds_write2_b32 v3, v6, v7 offset1:1
	ds_write2_b32 v3, v8, v9 offset0:2 offset1:3
	v_lshlrev_b64 v[6:7], 12, v[0:1]
	v_lshl_add_u64 v[6:7], v[18:19], 0, v[6:7]
	global_load_dwordx4 v[6:9], v[6:7], off
	v_add_u32_e32 v0, 0x420, v3
	s_waitcnt vmcnt(0)
	ds_write2_b32 v0, v6, v7 offset1:1
	v_add_u32_e32 v0, 0x428, v3
	ds_write2_b32 v0, v8, v9 offset1:1
	v_or_b32_e32 v0, v2, v27
	v_lshlrev_b64 v[6:7], 12, v[0:1]
	v_lshl_add_u64 v[6:7], v[18:19], 0, v[6:7]
	global_load_dwordx4 v[6:9], v[6:7], off
	v_add_u32_e32 v0, 0x840, v3
	s_waitcnt vmcnt(0)
	ds_write2_b32 v0, v6, v7 offset1:1
	v_add_u32_e32 v0, 0x848, v3
	ds_write2_b32 v0, v8, v9 offset1:1
	v_or_b32_e32 v0, v2, v29
	v_lshlrev_b64 v[6:7], 12, v[0:1]
	v_lshl_add_u64 v[6:7], v[18:19], 0, v[6:7]
	global_load_dwordx4 v[6:9], v[6:7], off
	v_add_u32_e32 v0, 0xc60, v3
	s_waitcnt vmcnt(0)
	ds_write2_b32 v0, v6, v7 offset1:1
	v_add_u32_e32 v0, 0xc68, v3
	ds_write2_b32 v0, v8, v9 offset1:1
	v_or_b32_e32 v0, v2, v30
	v_lshlrev_b64 v[6:7], 12, v[0:1]
	v_lshl_add_u64 v[6:7], v[18:19], 0, v[6:7]
	global_load_dwordx4 v[6:9], v[6:7], off
	v_add_u32_e32 v0, 0x1080, v3
	s_waitcnt vmcnt(0)
	ds_write2_b32 v0, v6, v7 offset1:1
	v_add_u32_e32 v0, 0x1088, v3
	ds_write2_b32 v0, v8, v9 offset1:1
	v_or_b32_e32 v0, v2, v31
	v_lshlrev_b64 v[6:7], 12, v[0:1]
	v_lshl_add_u64 v[6:7], v[18:19], 0, v[6:7]
	global_load_dwordx4 v[6:9], v[6:7], off
	v_add_u32_e32 v0, 0x14a0, v3
	s_waitcnt vmcnt(0)
	ds_write2_b32 v0, v6, v7 offset1:1
	v_add_u32_e32 v0, 0x14a8, v3
	ds_write2_b32 v0, v8, v9 offset1:1
	v_or_b32_e32 v0, v2, v32
	v_lshlrev_b64 v[6:7], 12, v[0:1]
	v_lshl_add_u64 v[6:7], v[18:19], 0, v[6:7]
	global_load_dwordx4 v[6:9], v[6:7], off
	v_add_u32_e32 v0, 0x18c0, v3
	s_waitcnt vmcnt(0)
	ds_write2_b32 v0, v6, v7 offset1:1
	v_add_u32_e32 v0, 0x18c8, v3
	ds_write2_b32 v0, v8, v9 offset1:1
	v_or_b32_e32 v0, v2, v33
	v_lshlrev_b64 v[6:7], 12, v[0:1]
	v_lshl_add_u64 v[6:7], v[18:19], 0, v[6:7]
	global_load_dwordx4 v[6:9], v[6:7], off
	v_add_u32_e32 v0, 0x1ce0, v3
	s_waitcnt vmcnt(0)
	ds_write2_b32 v0, v6, v7 offset1:1
	v_add_u32_e32 v0, 0x1ce8, v3
	ds_write2_b32 v0, v8, v9 offset1:1
	s_waitcnt lgkmcnt(0)
	v_mov_b32_e32 v3, v1
	v_lshl_add_u64 v[2:3], v[2:3], 1, v[16:17]
	ds_read2_b32 v[16:17], v34 offset0:33 offset1:41
	ds_read2_b32 v[18:19], v34 offset1:8
	v_lshlrev_b32_e32 v0, 1, v14
	ds_read2_b32 v[20:21], v34 offset0:66 offset1:74
	ds_read2_b32 v[22:23], v34 offset0:99 offset1:107
	v_lshl_add_u64 v[2:3], v[2:3], 0, v[0:1]
	s_waitcnt lgkmcnt(3)
	v_bfe_u32 v5, v16, 16, 1
	s_waitcnt lgkmcnt(2)
	v_bfe_u32 v0, v18, 16, 1
	v_add3_u32 v0, v18, v0, s91
	v_lshrrev_b32_e32 v0, 16, v0
	v_add3_u32 v5, v16, v5, s91
	ds_read2_b32 v[36:37], v34 offset0:132 offset1:140
	ds_read2_b32 v[38:39], v34 offset0:165 offset1:173
	v_and_or_b32 v6, v5, s92, v0
	s_waitcnt lgkmcnt(3)
	v_bfe_u32 v0, v20, 16, 1
	v_add3_u32 v0, v20, v0, s91
	s_waitcnt lgkmcnt(2)
	v_bfe_u32 v5, v22, 16, 1
	v_lshrrev_b32_e32 v0, 16, v0
	v_add3_u32 v5, v22, v5, s91
	ds_read2_b32 v[40:41], v34 offset0:198 offset1:206
	ds_read2_b32 v[42:43], v34 offset0:231 offset1:239
	v_and_or_b32 v7, v5, s92, v0
	s_waitcnt lgkmcnt(3)
	v_bfe_u32 v0, v36, 16, 1
	v_add3_u32 v0, v36, v0, s91
	s_waitcnt lgkmcnt(2)
	v_bfe_u32 v5, v38, 16, 1
	v_lshrrev_b32_e32 v0, 16, v0
	v_add3_u32 v5, v38, v5, s91
	v_and_or_b32 v8, v5, s92, v0
	s_waitcnt lgkmcnt(1)
	v_bfe_u32 v0, v40, 16, 1
	v_add3_u32 v0, v40, v0, s91
	s_waitcnt lgkmcnt(0)
	v_bfe_u32 v5, v42, 16, 1
	v_lshrrev_b32_e32 v0, 16, v0
	v_add3_u32 v5, v42, v5, s91
	v_and_or_b32 v9, v5, s92, v0
	v_or_b32_e32 v0, v4, v10
	v_mul_u32_u24_e32 v0, 0xb00, v0
	v_lshl_add_u64 v[2:3], v[2:3], 0, s[4:5]
	v_lshlrev_b32_e32 v0, 1, v0
	v_lshl_add_u64 v[44:45], v[2:3], 0, v[0:1]
	v_bfe_u32 v0, v19, 16, 1
	v_add3_u32 v0, v19, v0, s91
	v_bfe_u32 v5, v17, 16, 1
	v_lshrrev_b32_e32 v0, 16, v0
	v_add3_u32 v5, v17, v5, s91
	global_store_dwordx4 v[44:45], v[6:9], off
	s_nop 1
	v_and_or_b32 v6, v5, s92, v0
	v_bfe_u32 v0, v21, 16, 1
	v_add3_u32 v0, v21, v0, s91
	v_bfe_u32 v5, v23, 16, 1
	v_lshrrev_b32_e32 v0, 16, v0
	v_add3_u32 v5, v23, v5, s91
	v_and_or_b32 v7, v5, s92, v0
	v_bfe_u32 v0, v37, 16, 1
	v_add3_u32 v0, v37, v0, s91
	v_bfe_u32 v5, v39, 16, 1
	v_lshrrev_b32_e32 v0, 16, v0
	v_add3_u32 v5, v39, v5, s91
	v_and_or_b32 v8, v5, s92, v0
	v_bfe_u32 v0, v41, 16, 1
	v_add3_u32 v0, v41, v0, s91
	v_bfe_u32 v5, v43, 16, 1
	v_lshrrev_b32_e32 v0, 16, v0
	v_add3_u32 v5, v43, v5, s91
	v_and_or_b32 v9, v5, s92, v0
	v_or_b32_e32 v0, v4, v25
	v_mul_u32_u24_e32 v0, 0xb00, v0
	v_lshlrev_b32_e32 v0, 1, v0
	v_lshl_add_u64 v[16:17], v[2:3], 0, v[0:1]
	global_store_dwordx4 v[16:17], v[6:9], off
	ds_read2_b32 v[16:17], v34 offset0:16 offset1:24
	ds_read2_b32 v[18:19], v34 offset0:49 offset1:57
	ds_read2_b32 v[20:21], v34 offset0:82 offset1:90
	ds_read2_b32 v[22:23], v34 offset0:115 offset1:123
	ds_read2_b32 v[36:37], v34 offset0:148 offset1:156
	ds_read2_b32 v[38:39], v34 offset0:181 offset1:189
	ds_read2_b32 v[40:41], v34 offset0:214 offset1:222
	ds_read2_b32 v[42:43], v34 offset0:247 offset1:255
	s_waitcnt lgkmcnt(7)
	v_bfe_u32 v0, v16, 16, 1
	v_add3_u32 v0, v16, v0, s91
	s_waitcnt lgkmcnt(6)
	v_bfe_u32 v5, v18, 16, 1
	v_lshrrev_b32_e32 v0, 16, v0
	v_add3_u32 v5, v18, v5, s91
	v_and_or_b32 v6, v5, s92, v0
	s_waitcnt lgkmcnt(5)
	v_bfe_u32 v0, v20, 16, 1
	v_add3_u32 v0, v20, v0, s91
	s_waitcnt lgkmcnt(4)
	v_bfe_u32 v5, v22, 16, 1
	v_lshrrev_b32_e32 v0, 16, v0
	v_add3_u32 v5, v22, v5, s91
	v_and_or_b32 v7, v5, s92, v0
	s_waitcnt lgkmcnt(3)
	v_bfe_u32 v0, v36, 16, 1
	v_add3_u32 v0, v36, v0, s91
	s_waitcnt lgkmcnt(2)
	v_bfe_u32 v5, v38, 16, 1
	v_lshrrev_b32_e32 v0, 16, v0
	v_add3_u32 v5, v38, v5, s91
	v_and_or_b32 v8, v5, s92, v0
	s_waitcnt lgkmcnt(1)
	v_bfe_u32 v0, v40, 16, 1
	v_add3_u32 v0, v40, v0, s91
	s_waitcnt lgkmcnt(0)
	v_bfe_u32 v5, v42, 16, 1
	v_lshrrev_b32_e32 v0, 16, v0
	v_add3_u32 v5, v42, v5, s91
	v_and_or_b32 v9, v5, s92, v0
	v_or_b32_e32 v0, v4, v27
	v_mul_u32_u24_e32 v0, 0xb00, v0
	v_lshlrev_b32_e32 v0, 1, v0
	v_lshl_add_u64 v[44:45], v[2:3], 0, v[0:1]
	v_bfe_u32 v0, v17, 16, 1
	v_add3_u32 v0, v17, v0, s91
	v_bfe_u32 v5, v19, 16, 1
	v_lshrrev_b32_e32 v0, 16, v0
	v_add3_u32 v5, v19, v5, s91
	global_store_dwordx4 v[44:45], v[6:9], off
	s_nop 1
	v_and_or_b32 v6, v5, s92, v0
	v_bfe_u32 v0, v21, 16, 1
	v_add3_u32 v0, v21, v0, s91
	v_bfe_u32 v5, v23, 16, 1
	v_lshrrev_b32_e32 v0, 16, v0
	v_add3_u32 v5, v23, v5, s91
	v_and_or_b32 v7, v5, s92, v0
	v_bfe_u32 v0, v37, 16, 1
	v_add3_u32 v0, v37, v0, s91
	v_bfe_u32 v5, v39, 16, 1
	v_lshrrev_b32_e32 v0, 16, v0
	v_add3_u32 v5, v39, v5, s91
	v_and_or_b32 v8, v5, s92, v0
	v_bfe_u32 v0, v41, 16, 1
	v_add3_u32 v0, v41, v0, s91
	v_bfe_u32 v5, v43, 16, 1
	v_lshrrev_b32_e32 v0, 16, v0
	v_add3_u32 v5, v43, v5, s91
	v_and_or_b32 v9, v5, s92, v0
	v_or_b32_e32 v0, v4, v29
	v_mul_u32_u24_e32 v0, 0xb00, v0
	v_lshlrev_b32_e32 v0, 1, v0
	v_lshl_add_u64 v[2:3], v[2:3], 0, v[0:1]
	global_store_dwordx4 v[2:3], v[6:9], off
	s_waitcnt lgkmcnt(0)

.LBB0_902:
	v_readlane_b32 s0, v254, 21
	v_readlane_b32 s1, v254, 22
	s_mov_b64 s[24:25], s[76:77]
	v_mov_b32_e32 v0, v204
	s_andn2_b64 vcc, exec, s[0:1]
	s_cbranch_vccnz .LBB0_1025
	v_ashrrev_i32_e32 v2, 6, v0
	v_readlane_b32 s0, v254, 23
	s_nop 1
	v_add_u32_e32 v11, s0, v2
	s_movk_i32 s0, 0xc80
	v_cmp_gt_i32_e32 vcc, s0, v11
	s_and_saveexec_b64 s[44:45], vcc
	s_cbranch_execz .LBB0_1024
	v_and_b32_e32 v10, 63, v0
	v_bfe_u32 v12, v0, 3, 3
	v_lshlrev_b32_e32 v3, 2, v0
	v_lshlrev_b32_e32 v0, 3, v0
	v_and_b32_e32 v14, 28, v3
	s_movk_i32 s0, 0x84
	v_mov_b32_e32 v3, 0x840
	v_and_b32_e32 v16, 56, v0
	v_lshl_add_u32 v2, v2, 14, 0
	v_mad_u32_u24 v29, v12, s0, v3
	v_mul_u32_u24_e32 v0, 0x84, v16
	v_lshlrev_b32_e32 v3, 2, v12
	v_lshl_add_u32 v15, v14, 2, v2
	v_mul_u32_u24_e32 v17, 0x84, v12
	v_or_b32_e32 v26, 8, v12
	v_mad_u32_u24 v27, v12, s0, v252
	v_or_b32_e32 v28, 16, v12
	v_or_b32_e32 v30, 24, v12
	v_or_b32_e32 v31, 32, v12
	v_or_b32_e32 v32, 40, v12
	v_or_b32_e32 v33, 48, v12
	v_or_b32_e32 v34, 56, v12
	v_add3_u32 v35, v2, v0, v3
	v_mov_b32_e32 v13, v1
	s_mov_b64 s[46:47], 0
	s_branch .LBB0_908

.LBB0_907:
	s_or_b64 exec, exec, s[48:49]
	v_readlane_b32 s0, v254, 24
	s_nop 1
	v_add_u32_e32 v11, s0, v11
	s_movk_i32 s0, 0xc7f
	v_cmp_lt_i32_e32 vcc, s0, v11
	s_or_b64 s[46:47], vcc, s[46:47]
	s_andn2_b64 exec, exec, s[46:47]
	s_cbranch_execz .LBB0_1024
